# P0 (adaLN mod + first weight copies) stores write-through so the seam-0 leader's L2 writeback finds little dirty data
# speedup vs baseline: 1.0078x; 1.0027x over previous
.LBB0_28:
	s_or_b64 exec, exec, s[4:5]
	s_waitcnt lgkmcnt(0)
	s_barrier
	s_and_saveexec_b64 s[4:5], s[0:1]
	s_cbranch_execz .LBB0_23
	s_lshl_b32 s61, s76, 6
	v_or_b32_e32 v2, s61, v222
	v_ashrrev_i32_e32 v3, 31, v2
	v_lshl_add_u64 v[2:3], v[2:3], 2, s[66:67]
	global_load_dword v12, v[2:3], off
	ds_read2st64_b32 v[2:3], v47 offset0:80 offset1:85
	ds_read2st64_b32 v[4:5], v47 offset0:90 offset1:95
	ds_read2st64_b32 v[6:7], v47 offset0:100 offset1:105
	ds_read2st64_b32 v[8:9], v47 offset0:110 offset1:115
	v_add_u32_e32 v10, s61, v45
	s_waitcnt lgkmcnt(3)
	v_add_f32_e32 v2, 0, v2
	v_add_f32_e32 v2, v2, v3
	s_waitcnt lgkmcnt(2)
	v_add_f32_e32 v2, v2, v4
	v_add_f32_e32 v2, v2, v5
	s_waitcnt lgkmcnt(1)
	v_add_f32_e32 v2, v2, v6
	v_add_f32_e32 v2, v2, v7
	s_waitcnt lgkmcnt(0)
	v_add_f32_e32 v2, v2, v8
	v_ashrrev_i32_e32 v11, 31, v10
	v_add_f32_e32 v2, v2, v9
	s_waitcnt vmcnt(0)
	v_add_f32_e32 v4, v2, v12
	v_lshl_add_u64 v[2:3], v[10:11], 2, s[72:73]
	global_store_dword v[2:3], v4, off sc0 sc1
	s_branch .LBB0_23

.LBB0_34:
	s_cmpk_gt_i32 s3, 0xaff
	s_mov_b64 s[4:5], -1
	s_cbranch_scc0 .LBB0_40
	s_cmpk_gt_u32 s3, 0x12ff
	s_cbranch_scc0 .LBB0_37
	s_and_b32 s5, s39, 0x1ffc0
	s_and_b32 s4, s11, 0x3e0
	s_lshl_b32 s0, s4, 2
	v_or_b32_e32 v0, s5, v14
	v_lshl_add_u64 v[62:63], v[8:9], 0, s[0:1]
	v_lshlrev_b32_e32 v0, 12, v0
	v_lshl_add_u64 v[64:65], v[62:63], 0, v[0:1]
	v_or_b32_e32 v0, s5, v16
	v_lshlrev_b32_e32 v0, 12, v0
	v_lshl_add_u64 v[66:67], v[62:63], 0, v[0:1]
	v_or_b32_e32 v0, s5, v17
	v_lshlrev_b32_e32 v0, 12, v0
	v_lshl_add_u64 v[68:69], v[62:63], 0, v[0:1]
	v_or_b32_e32 v0, s5, v18
	v_lshlrev_b32_e32 v0, 12, v0
	v_lshl_add_u64 v[70:71], v[62:63], 0, v[0:1]
	v_or_b32_e32 v0, s5, v19
	v_lshlrev_b32_e32 v0, 12, v0
	v_lshl_add_u64 v[72:73], v[62:63], 0, v[0:1]
	v_or_b32_e32 v0, s5, v20
	v_lshlrev_b32_e32 v0, 12, v0
	v_lshl_add_u64 v[74:75], v[62:63], 0, v[0:1]
	v_or_b32_e32 v0, s5, v21
	v_lshlrev_b32_e32 v0, 12, v0
	v_lshl_add_u64 v[76:77], v[62:63], 0, v[0:1]
	v_or_b32_e32 v0, s5, v22
	v_lshlrev_b32_e32 v0, 12, v0
	v_lshl_add_u64 v[78:79], v[62:63], 0, v[0:1]
	v_or_b32_e32 v0, s5, v23
	v_lshlrev_b32_e32 v0, 12, v0
	global_load_dword v80, v[64:65], off nt
	global_load_dword v81, v[66:67], off nt
	global_load_dword v82, v[68:69], off nt
	global_load_dword v83, v[70:71], off nt
	global_load_dword v84, v[72:73], off nt
	global_load_dword v85, v[74:75], off nt
	global_load_dword v86, v[76:77], off nt
	global_load_dword v87, v[78:79], off nt
	v_lshl_add_u64 v[64:65], v[62:63], 0, v[0:1]
	v_or_b32_e32 v0, s5, v24
	v_lshlrev_b32_e32 v0, 12, v0
	v_lshl_add_u64 v[66:67], v[62:63], 0, v[0:1]
	v_or_b32_e32 v0, s5, v25
	v_lshlrev_b32_e32 v0, 12, v0
	v_lshl_add_u64 v[68:69], v[62:63], 0, v[0:1]
	v_or_b32_e32 v0, s5, v26
	v_lshlrev_b32_e32 v0, 12, v0
	v_lshl_add_u64 v[70:71], v[62:63], 0, v[0:1]
	v_or_b32_e32 v0, s5, v27
	v_lshlrev_b32_e32 v0, 12, v0
	v_lshl_add_u64 v[72:73], v[62:63], 0, v[0:1]
	v_or_b32_e32 v0, s5, v29
	v_lshlrev_b32_e32 v0, 12, v0
	v_lshl_add_u64 v[74:75], v[62:63], 0, v[0:1]
	v_or_b32_e32 v0, s5, v30
	v_lshlrev_b32_e32 v0, 12, v0
	v_lshl_add_u64 v[76:77], v[62:63], 0, v[0:1]
	v_or_b32_e32 v0, s5, v31
	v_lshlrev_b32_e32 v0, 12, v0
	v_lshl_add_u64 v[78:79], v[62:63], 0, v[0:1]
	v_or_b32_e32 v0, s5, v32
	v_lshlrev_b32_e32 v0, 12, v0
	global_load_dword v88, v[64:65], off nt
	global_load_dword v89, v[66:67], off nt
	global_load_dword v90, v[68:69], off nt
	global_load_dword v91, v[70:71], off nt
	global_load_dword v92, v[72:73], off nt
	global_load_dword v93, v[74:75], off nt
	global_load_dword v94, v[76:77], off nt
	global_load_dword v95, v[78:79], off nt
	v_lshl_add_u64 v[64:65], v[62:63], 0, v[0:1]
	v_or_b32_e32 v0, s5, v33
	v_lshlrev_b32_e32 v0, 12, v0
	v_lshl_add_u64 v[66:67], v[62:63], 0, v[0:1]
	v_or_b32_e32 v0, s5, v34
	v_lshlrev_b32_e32 v0, 12, v0
	v_lshl_add_u64 v[68:69], v[62:63], 0, v[0:1]
	v_or_b32_e32 v0, s5, v36
	v_lshlrev_b32_e32 v0, 12, v0
	v_lshl_add_u64 v[70:71], v[62:63], 0, v[0:1]
	v_or_b32_e32 v0, s5, v37
	v_lshlrev_b32_e32 v0, 12, v0
	v_lshl_add_u64 v[72:73], v[62:63], 0, v[0:1]
	v_or_b32_e32 v0, s5, v38
	v_lshlrev_b32_e32 v0, 12, v0
	v_lshl_add_u64 v[74:75], v[62:63], 0, v[0:1]
	v_or_b32_e32 v0, s5, v39
	v_lshlrev_b32_e32 v0, 12, v0
	v_lshl_add_u64 v[76:77], v[62:63], 0, v[0:1]
	v_or_b32_e32 v0, s5, v40
	v_lshlrev_b32_e32 v0, 12, v0
	v_lshl_add_u64 v[78:79], v[62:63], 0, v[0:1]
	v_or_b32_e32 v0, s5, v41
	v_lshlrev_b32_e32 v0, 12, v0
	global_load_dword v96, v[64:65], off nt
	global_load_dword v97, v[66:67], off nt
	global_load_dword v98, v[68:69], off nt
	global_load_dword v99, v[70:71], off nt
	global_load_dword v100, v[72:73], off nt
	global_load_dword v101, v[74:75], off nt
	global_load_dword v102, v[76:77], off nt
	s_nop 0
	global_load_dword v78, v[78:79], off nt
	v_lshl_add_u64 v[64:65], v[62:63], 0, v[0:1]
	v_or_b32_e32 v0, s5, v42
	v_lshlrev_b32_e32 v0, 12, v0
	v_lshl_add_u64 v[66:67], v[62:63], 0, v[0:1]
	v_or_b32_e32 v0, s5, v43
	v_lshlrev_b32_e32 v0, 12, v0
	v_lshl_add_u64 v[68:69], v[62:63], 0, v[0:1]
	v_or_b32_e32 v0, s5, v44
	v_lshlrev_b32_e32 v0, 12, v0
	v_lshl_add_u64 v[70:71], v[62:63], 0, v[0:1]
	v_or_b32_e32 v0, s5, v45
	v_lshlrev_b32_e32 v0, 12, v0
	v_lshl_add_u64 v[72:73], v[62:63], 0, v[0:1]
	v_or_b32_e32 v0, s5, v46
	v_lshlrev_b32_e32 v0, 12, v0
	v_lshl_add_u64 v[74:75], v[62:63], 0, v[0:1]
	v_or_b32_e32 v0, s5, v47
	v_lshlrev_b32_e32 v0, 12, v0
	v_lshl_add_u64 v[76:77], v[62:63], 0, v[0:1]
	v_or_b32_e32 v0, s5, v48
	v_lshlrev_b32_e32 v0, 12, v0
	v_lshl_add_u64 v[62:63], v[62:63], 0, v[0:1]
	global_load_dword v0, v[64:65], off nt
	s_nop 0
	global_load_dword v64, v[66:67], off nt
	global_load_dword v65, v[68:69], off nt
	s_nop 0
	global_load_dword v66, v[70:71], off nt
	global_load_dword v67, v[72:73], off nt
	global_load_dword v68, v[74:75], off nt
	global_load_dword v69, v[76:77], off nt
	s_nop 0
	global_load_dword v62, v[62:63], off nt
	v_add_u32_e32 v63, 0x400, v56
	s_lshl_b32 s0, s5, 1
	s_waitcnt vmcnt(30)
	ds_write2_b32 v54, v80, v81 offset1:66
	s_waitcnt vmcnt(28)
	ds_write2_b32 v54, v82, v83 offset0:132 offset1:198
	s_waitcnt vmcnt(26)
	ds_write2_b32 v55, v84, v85 offset0:8 offset1:74
	s_waitcnt vmcnt(24)
	ds_write2_b32 v56, v86, v87 offset1:66
	s_waitcnt vmcnt(22)
	ds_write2_b32 v56, v88, v89 offset0:132 offset1:198
	s_waitcnt vmcnt(20)
	ds_write2_b32 v63, v90, v91 offset0:8 offset1:74
	v_add_u32_e32 v63, v15, v28
	s_waitcnt vmcnt(18)
	ds_write2_b32 v63, v92, v93 offset1:66
	s_waitcnt vmcnt(16)
	ds_write2_b32 v63, v94, v95 offset0:132 offset1:198
	v_add_u32_e32 v63, 0x400, v63
	s_waitcnt vmcnt(14)
	ds_write2_b32 v63, v96, v97 offset0:8 offset1:74
	v_add_u32_e32 v63, v15, v35
	v_add_u32_e32 v70, 0x400, v63
	s_waitcnt vmcnt(12)
	ds_write2_b32 v63, v98, v99 offset1:66
	s_waitcnt vmcnt(10)
	ds_write2_b32 v63, v100, v101 offset0:132 offset1:198
	s_waitcnt vmcnt(8)
	ds_write2_b32 v70, v102, v78 offset0:8 offset1:74
	s_waitcnt vmcnt(6)
	ds_write2_b32 v70, v0, v64 offset0:140 offset1:206
	v_add_u32_e32 v0, 0x800, v63
	s_waitcnt vmcnt(4)
	ds_write2_b32 v0, v65, v66 offset0:16 offset1:82
	s_waitcnt vmcnt(2)
	ds_write2_b32 v0, v67, v68 offset0:148 offset1:214
	v_add_u32_e32 v0, 0xc00, v63
	s_waitcnt vmcnt(0)
	ds_write2_b32 v0, v69, v62 offset0:24 offset1:90
	s_waitcnt lgkmcnt(0)
	ds_read2_b32 v[66:67], v50 offset1:8
	ds_read2_b32 v[70:71], v50 offset0:33 offset1:41
	ds_read2_b32 v[72:73], v50 offset0:66 offset1:74
	ds_read2_b32 v[74:75], v50 offset0:99 offset1:107
	ds_read2_b32 v[76:77], v50 offset0:132 offset1:140
	s_waitcnt lgkmcnt(4)
	v_bfe_u32 v0, v66, 16, 1
	v_add3_u32 v0, v66, v0, s62
	s_waitcnt lgkmcnt(3)
	v_bfe_u32 v62, v70, 16, 1
	v_lshrrev_b32_e32 v0, 16, v0
	v_add3_u32 v62, v70, v62, s62
	ds_read2_b32 v[78:79], v50 offset0:165 offset1:173
	v_and_or_b32 v62, v62, s63, v0
	s_waitcnt lgkmcnt(3)
	v_bfe_u32 v0, v72, 16, 1
	v_add3_u32 v0, v72, v0, s62
	s_waitcnt lgkmcnt(2)
	v_bfe_u32 v63, v74, 16, 1
	ds_read2_b32 v[80:81], v50 offset0:198 offset1:206
	v_lshrrev_b32_e32 v0, 16, v0
	v_add3_u32 v63, v74, v63, s62
	ds_read2_b32 v[82:83], v50 offset0:231 offset1:239
	v_and_or_b32 v63, v63, s63, v0
	s_waitcnt lgkmcnt(3)
	v_bfe_u32 v0, v76, 16, 1
	v_add3_u32 v0, v76, v0, s62
	s_waitcnt lgkmcnt(2)
	v_bfe_u32 v64, v78, 16, 1
	v_lshrrev_b32_e32 v0, 16, v0
	v_add3_u32 v64, v78, v64, s62
	v_and_or_b32 v64, v64, s63, v0
	s_waitcnt lgkmcnt(1)
	v_bfe_u32 v0, v80, 16, 1
	v_add3_u32 v0, v80, v0, s62
	s_waitcnt lgkmcnt(0)
	v_bfe_u32 v65, v82, 16, 1
	v_lshrrev_b32_e32 v0, 16, v0
	v_add3_u32 v65, v82, v65, s62
	v_and_or_b32 v65, v65, s63, v0
	v_or_b32_e32 v0, s4, v49
	v_mul_u32_u24_e32 v0, 0xb00, v0
	v_lshl_add_u64 v[68:69], v[4:5], 0, s[0:1]
	v_lshlrev_b32_e32 v0, 1, v0
	v_lshl_add_u64 v[84:85], v[68:69], 0, v[0:1]
	v_bfe_u32 v0, v67, 16, 1
	global_store_dwordx4 v[84:85], v[62:65], off sc0 sc1
	v_add3_u32 v0, v67, v0, s62
	v_lshrrev_b32_e32 v0, 16, v0
	v_bfe_u32 v62, v71, 16, 1
	v_add3_u32 v62, v71, v62, s62
	v_and_or_b32 v62, v62, s63, v0
	v_bfe_u32 v0, v73, 16, 1
	v_add3_u32 v0, v73, v0, s62
	v_bfe_u32 v63, v75, 16, 1
	v_lshrrev_b32_e32 v0, 16, v0
	v_add3_u32 v63, v75, v63, s62
	v_and_or_b32 v63, v63, s63, v0
	v_bfe_u32 v0, v77, 16, 1
	v_add3_u32 v0, v77, v0, s62
	v_bfe_u32 v64, v79, 16, 1
	v_lshrrev_b32_e32 v0, 16, v0
	v_add3_u32 v64, v79, v64, s62
	v_and_or_b32 v64, v64, s63, v0
	v_bfe_u32 v0, v81, 16, 1
	v_add3_u32 v0, v81, v0, s62
	v_bfe_u32 v65, v83, 16, 1
	v_lshrrev_b32_e32 v0, 16, v0
	v_add3_u32 v65, v83, v65, s62
	v_and_or_b32 v65, v65, s63, v0
	v_or_b32_e32 v0, s4, v51
	v_mul_u32_u24_e32 v0, 0xb00, v0
	v_lshlrev_b32_e32 v0, 1, v0
	ds_read2_b32 v[66:67], v50 offset0:16 offset1:24
	v_lshl_add_u64 v[70:71], v[68:69], 0, v[0:1]
	global_store_dwordx4 v[70:71], v[62:65], off sc0 sc1
	ds_read2_b32 v[70:71], v50 offset0:49 offset1:57
	ds_read2_b32 v[72:73], v50 offset0:82 offset1:90
	ds_read2_b32 v[74:75], v50 offset0:115 offset1:123
	s_waitcnt lgkmcnt(3)
	v_bfe_u32 v0, v66, 16, 1
	v_add3_u32 v0, v66, v0, s62
	s_waitcnt lgkmcnt(2)
	v_bfe_u32 v62, v70, 16, 1
	ds_read2_b32 v[76:77], v50 offset0:148 offset1:156
	v_lshrrev_b32_e32 v0, 16, v0
	v_add3_u32 v62, v70, v62, s62
	ds_read2_b32 v[78:79], v50 offset0:181 offset1:189
	v_and_or_b32 v62, v62, s63, v0
	s_waitcnt lgkmcnt(3)
	v_bfe_u32 v0, v72, 16, 1
	v_add3_u32 v0, v72, v0, s62
	s_waitcnt lgkmcnt(2)
	v_bfe_u32 v63, v74, 16, 1
	ds_read2_b32 v[80:81], v50 offset0:214 offset1:222
	v_lshrrev_b32_e32 v0, 16, v0
	v_add3_u32 v63, v74, v63, s62
	ds_read2_b32 v[82:83], v50 offset0:247 offset1:255
	v_and_or_b32 v63, v63, s63, v0
	s_waitcnt lgkmcnt(3)
	v_bfe_u32 v0, v76, 16, 1
	v_add3_u32 v0, v76, v0, s62
	s_waitcnt lgkmcnt(2)
	v_bfe_u32 v64, v78, 16, 1
	v_lshrrev_b32_e32 v0, 16, v0
	v_add3_u32 v64, v78, v64, s62
	v_and_or_b32 v64, v64, s63, v0
	s_waitcnt lgkmcnt(1)
	v_bfe_u32 v0, v80, 16, 1
	v_add3_u32 v0, v80, v0, s62
	s_waitcnt lgkmcnt(0)
	v_bfe_u32 v65, v82, 16, 1
	v_lshrrev_b32_e32 v0, 16, v0
	v_add3_u32 v65, v82, v65, s62
	v_and_or_b32 v65, v65, s63, v0
	v_or_b32_e32 v0, s4, v52
	v_mul_u32_u24_e32 v0, 0xb00, v0
	v_lshlrev_b32_e32 v0, 1, v0
	v_lshl_add_u64 v[84:85], v[68:69], 0, v[0:1]
	global_store_dwordx4 v[84:85], v[62:65], off sc0 sc1
	v_or_b32_e32 v0, s4, v53
	v_bfe_u32 v66, v81, 16, 1
	v_bfe_u32 v63, v67, 16, 1
	v_bfe_u32 v62, v71, 16, 1
	v_add3_u32 v63, v67, v63, s62
	v_add3_u32 v62, v71, v62, s62
	v_lshrrev_b32_e32 v63, 16, v63
	v_bfe_u32 v64, v73, 16, 1
	v_and_or_b32 v62, v62, s63, v63
	v_bfe_u32 v63, v75, 16, 1
	v_add3_u32 v64, v73, v64, s62
	v_add3_u32 v63, v75, v63, s62
	v_lshrrev_b32_e32 v64, 16, v64
	v_bfe_u32 v65, v77, 16, 1
	v_and_or_b32 v63, v63, s63, v64
	v_bfe_u32 v64, v79, 16, 1
	v_add3_u32 v65, v77, v65, s62
	v_add3_u32 v64, v79, v64, s62
	v_lshrrev_b32_e32 v65, 16, v65
	v_and_or_b32 v64, v64, s63, v65
	v_bfe_u32 v65, v83, 16, 1
	v_add3_u32 v66, v81, v66, s62
	v_mul_u32_u24_e32 v0, 0xb00, v0
	v_add3_u32 v65, v83, v65, s62
	v_lshrrev_b32_e32 v66, 16, v66
	v_lshlrev_b32_e32 v0, 1, v0
	v_and_or_b32 v65, v65, s63, v66
	v_lshl_add_u64 v[66:67], v[68:69], 0, v[0:1]
	global_store_dwordx4 v[66:67], v[62:65], off sc0 sc1
	s_waitcnt lgkmcnt(0)
	s_mov_b64 s[4:5], 0
.LBB0_37:
	s_andn2_b64 vcc, exec, s[4:5]
	s_cbranch_vccnz .LBB0_39
	s_add_i32 s0, s3, 0xf500
	s_lshr_b32 s0, s0, 1
	s_and_b32 s5, s0, 0x7fc0
	s_and_b32 s4, s11, 0xfe0
	s_lshl_b32 s0, s4, 2
	v_or_b32_e32 v0, s5, v14
	v_lshl_add_u64 v[62:63], v[10:11], 0, s[0:1]
	v_lshlrev_b32_e32 v0, 14, v0
	v_lshl_add_u64 v[64:65], v[62:63], 0, v[0:1]
	v_or_b32_e32 v0, s5, v16
	v_lshlrev_b32_e32 v0, 14, v0
	v_lshl_add_u64 v[66:67], v[62:63], 0, v[0:1]
	v_or_b32_e32 v0, s5, v17
	v_lshlrev_b32_e32 v0, 14, v0
	v_lshl_add_u64 v[68:69], v[62:63], 0, v[0:1]
	v_or_b32_e32 v0, s5, v18
	v_lshlrev_b32_e32 v0, 14, v0
	v_lshl_add_u64 v[70:71], v[62:63], 0, v[0:1]
	v_or_b32_e32 v0, s5, v19
	v_lshlrev_b32_e32 v0, 14, v0
	v_lshl_add_u64 v[72:73], v[62:63], 0, v[0:1]
	v_or_b32_e32 v0, s5, v20
	v_lshlrev_b32_e32 v0, 14, v0
	v_lshl_add_u64 v[74:75], v[62:63], 0, v[0:1]
	v_or_b32_e32 v0, s5, v21
	v_lshlrev_b32_e32 v0, 14, v0
	v_lshl_add_u64 v[76:77], v[62:63], 0, v[0:1]
	v_or_b32_e32 v0, s5, v22
	v_lshlrev_b32_e32 v0, 14, v0
	v_lshl_add_u64 v[78:79], v[62:63], 0, v[0:1]
	v_or_b32_e32 v0, s5, v23
	v_lshlrev_b32_e32 v0, 14, v0
	global_load_dword v80, v[64:65], off nt
	global_load_dword v81, v[66:67], off nt
	global_load_dword v82, v[68:69], off nt
	global_load_dword v83, v[70:71], off nt
	global_load_dword v84, v[72:73], off nt
	global_load_dword v85, v[74:75], off nt
	global_load_dword v86, v[76:77], off nt
	global_load_dword v87, v[78:79], off nt
	v_lshl_add_u64 v[64:65], v[62:63], 0, v[0:1]
	v_or_b32_e32 v0, s5, v24
	v_lshlrev_b32_e32 v0, 14, v0
	v_lshl_add_u64 v[66:67], v[62:63], 0, v[0:1]
	v_or_b32_e32 v0, s5, v25
	v_lshlrev_b32_e32 v0, 14, v0
	v_lshl_add_u64 v[68:69], v[62:63], 0, v[0:1]
	v_or_b32_e32 v0, s5, v26
	v_lshlrev_b32_e32 v0, 14, v0
	v_lshl_add_u64 v[70:71], v[62:63], 0, v[0:1]
	v_or_b32_e32 v0, s5, v27
	v_lshlrev_b32_e32 v0, 14, v0
	v_lshl_add_u64 v[72:73], v[62:63], 0, v[0:1]
	v_or_b32_e32 v0, s5, v29
	v_lshlrev_b32_e32 v0, 14, v0
	v_lshl_add_u64 v[74:75], v[62:63], 0, v[0:1]
	v_or_b32_e32 v0, s5, v30
	v_lshlrev_b32_e32 v0, 14, v0
	v_lshl_add_u64 v[76:77], v[62:63], 0, v[0:1]
	v_or_b32_e32 v0, s5, v31
	v_lshlrev_b32_e32 v0, 14, v0
	v_lshl_add_u64 v[78:79], v[62:63], 0, v[0:1]
	v_or_b32_e32 v0, s5, v32
	v_lshlrev_b32_e32 v0, 14, v0
	global_load_dword v88, v[64:65], off nt
	global_load_dword v89, v[66:67], off nt
	global_load_dword v90, v[68:69], off nt
	global_load_dword v91, v[70:71], off nt
	global_load_dword v92, v[72:73], off nt
	global_load_dword v93, v[74:75], off nt
	global_load_dword v94, v[76:77], off nt
	global_load_dword v95, v[78:79], off nt
	v_lshl_add_u64 v[64:65], v[62:63], 0, v[0:1]
	v_or_b32_e32 v0, s5, v33
	v_lshlrev_b32_e32 v0, 14, v0
	v_lshl_add_u64 v[66:67], v[62:63], 0, v[0:1]
	v_or_b32_e32 v0, s5, v34
	v_lshlrev_b32_e32 v0, 14, v0
	v_lshl_add_u64 v[68:69], v[62:63], 0, v[0:1]
	v_or_b32_e32 v0, s5, v36
	v_lshlrev_b32_e32 v0, 14, v0
	v_lshl_add_u64 v[70:71], v[62:63], 0, v[0:1]
	v_or_b32_e32 v0, s5, v37
	v_lshlrev_b32_e32 v0, 14, v0
	v_lshl_add_u64 v[72:73], v[62:63], 0, v[0:1]
	v_or_b32_e32 v0, s5, v38
	v_lshlrev_b32_e32 v0, 14, v0
	v_lshl_add_u64 v[74:75], v[62:63], 0, v[0:1]
	v_or_b32_e32 v0, s5, v39
	v_lshlrev_b32_e32 v0, 14, v0
	v_lshl_add_u64 v[76:77], v[62:63], 0, v[0:1]
	v_or_b32_e32 v0, s5, v40
	v_lshlrev_b32_e32 v0, 14, v0
	v_lshl_add_u64 v[78:79], v[62:63], 0, v[0:1]
	v_or_b32_e32 v0, s5, v41
	v_lshlrev_b32_e32 v0, 14, v0
	global_load_dword v96, v[64:65], off nt
	global_load_dword v97, v[66:67], off nt
	global_load_dword v98, v[68:69], off nt
	global_load_dword v99, v[70:71], off nt
	global_load_dword v100, v[72:73], off nt
	global_load_dword v101, v[74:75], off nt
	global_load_dword v102, v[76:77], off nt
	s_nop 0
	global_load_dword v78, v[78:79], off nt
	v_lshl_add_u64 v[64:65], v[62:63], 0, v[0:1]
	v_or_b32_e32 v0, s5, v42
	v_lshlrev_b32_e32 v0, 14, v0
	v_lshl_add_u64 v[66:67], v[62:63], 0, v[0:1]
	v_or_b32_e32 v0, s5, v43
	v_lshlrev_b32_e32 v0, 14, v0
	v_lshl_add_u64 v[68:69], v[62:63], 0, v[0:1]
	v_or_b32_e32 v0, s5, v44
	v_lshlrev_b32_e32 v0, 14, v0
	v_lshl_add_u64 v[70:71], v[62:63], 0, v[0:1]
	v_or_b32_e32 v0, s5, v45
	v_lshlrev_b32_e32 v0, 14, v0
	v_lshl_add_u64 v[72:73], v[62:63], 0, v[0:1]
	v_or_b32_e32 v0, s5, v46
	v_lshlrev_b32_e32 v0, 14, v0
	v_lshl_add_u64 v[74:75], v[62:63], 0, v[0:1]
	v_or_b32_e32 v0, s5, v47
	v_lshlrev_b32_e32 v0, 14, v0
	v_lshl_add_u64 v[76:77], v[62:63], 0, v[0:1]
	v_or_b32_e32 v0, s5, v48
	v_lshlrev_b32_e32 v0, 14, v0
	v_lshl_add_u64 v[62:63], v[62:63], 0, v[0:1]
	global_load_dword v0, v[64:65], off nt
	s_nop 0
	global_load_dword v64, v[66:67], off nt
	global_load_dword v65, v[68:69], off nt
	s_nop 0
	global_load_dword v66, v[70:71], off nt
	global_load_dword v67, v[72:73], off nt
	global_load_dword v68, v[74:75], off nt
	global_load_dword v69, v[76:77], off nt
	s_nop 0
	global_load_dword v62, v[62:63], off nt
	v_add_u32_e32 v63, 0x400, v56
	s_and_b32 s0, s41, 0x80
	s_and_b32 s8, s45, 0x60
	s_waitcnt vmcnt(30)
	ds_write2_b32 v54, v80, v81 offset1:66
	s_waitcnt vmcnt(28)
	ds_write2_b32 v54, v82, v83 offset0:132 offset1:198
	s_waitcnt vmcnt(26)
	ds_write2_b32 v55, v84, v85 offset0:8 offset1:74
	s_waitcnt vmcnt(24)
	ds_write2_b32 v56, v86, v87 offset1:66
	s_waitcnt vmcnt(22)
	ds_write2_b32 v56, v88, v89 offset0:132 offset1:198
	s_or_b32 s8, s8, s0
	s_waitcnt vmcnt(20)
	ds_write2_b32 v63, v90, v91 offset0:8 offset1:74
	v_add_u32_e32 v63, v15, v28
	s_waitcnt vmcnt(18)
	ds_write2_b32 v63, v92, v93 offset1:66
	s_waitcnt vmcnt(16)
	ds_write2_b32 v63, v94, v95 offset0:132 offset1:198
	v_add_u32_e32 v63, 0x400, v63
	s_lshl_b32 s0, s5, 1
	s_waitcnt vmcnt(14)
	ds_write2_b32 v63, v96, v97 offset0:8 offset1:74
	v_add_u32_e32 v63, v15, v35
	v_add_u32_e32 v70, 0x400, v63
	s_waitcnt vmcnt(12)
	ds_write2_b32 v63, v98, v99 offset1:66
	s_waitcnt vmcnt(10)
	ds_write2_b32 v63, v100, v101 offset0:132 offset1:198
	s_waitcnt vmcnt(8)
	ds_write2_b32 v70, v102, v78 offset0:8 offset1:74
	s_waitcnt vmcnt(6)
	ds_write2_b32 v70, v0, v64 offset0:140 offset1:206
	v_add_u32_e32 v0, 0x800, v63
	s_waitcnt vmcnt(4)
	ds_write2_b32 v0, v65, v66 offset0:16 offset1:82
	s_waitcnt vmcnt(2)
	ds_write2_b32 v0, v67, v68 offset0:148 offset1:214
	v_add_u32_e32 v0, 0xc00, v63
	s_waitcnt vmcnt(0)
	ds_write2_b32 v0, v69, v62 offset0:24 offset1:90
	s_waitcnt lgkmcnt(0)
	ds_read2_b32 v[66:67], v50 offset1:8
	ds_read2_b32 v[70:71], v50 offset0:33 offset1:41
	ds_read2_b32 v[72:73], v50 offset0:66 offset1:74
	ds_read2_b32 v[74:75], v50 offset0:99 offset1:107
	ds_read2_b32 v[76:77], v50 offset0:132 offset1:140
	s_waitcnt lgkmcnt(4)
	v_bfe_u32 v0, v66, 16, 1
	v_add3_u32 v0, v66, v0, s62
	s_waitcnt lgkmcnt(3)
	v_bfe_u32 v62, v70, 16, 1
	v_lshrrev_b32_e32 v0, 16, v0
	v_add3_u32 v62, v70, v62, s62
	ds_read2_b32 v[78:79], v50 offset0:165 offset1:173
	v_and_or_b32 v62, v62, s63, v0
	s_waitcnt lgkmcnt(3)
	v_bfe_u32 v0, v72, 16, 1
	v_add3_u32 v0, v72, v0, s62
	s_waitcnt lgkmcnt(2)
	v_bfe_u32 v63, v74, 16, 1
	ds_read2_b32 v[80:81], v50 offset0:198 offset1:206
	v_lshrrev_b32_e32 v0, 16, v0
	v_add3_u32 v63, v74, v63, s62
	ds_read2_b32 v[82:83], v50 offset0:231 offset1:239
	v_and_or_b32 v63, v63, s63, v0
	s_waitcnt lgkmcnt(3)
	v_bfe_u32 v0, v76, 16, 1
	v_add3_u32 v0, v76, v0, s62
	s_waitcnt lgkmcnt(2)
	v_bfe_u32 v64, v78, 16, 1
	v_lshrrev_b32_e32 v0, 16, v0
	v_add3_u32 v64, v78, v64, s62
	v_and_or_b32 v64, v64, s63, v0
	s_waitcnt lgkmcnt(1)
	v_bfe_u32 v0, v80, 16, 1
	v_lshl_add_u64 v[68:69], v[6:7], 0, s[0:1]
	v_add3_u32 v0, v80, v0, s62
	s_waitcnt lgkmcnt(0)
	v_bfe_u32 v65, v82, 16, 1
	s_add_i32 s0, s4, 0xfffffe00
	v_lshrrev_b32_e32 v0, 16, v0
	v_add3_u32 v65, v82, v65, s62
	s_cmpk_lt_u32 s0, 0x400
	v_bitop3_b32 v66, s4, v57, v49 bitop3:0xc8
	v_and_or_b32 v65, v65, s63, v0
	v_or_b32_e32 v0, s4, v49
	v_or_b32_e32 v66, s8, v66
	s_cselect_b64 vcc, -1, 0
	v_cndmask_b32_e32 v0, v0, v66, vcc
	v_lshlrev_b32_e32 v0, 11, v0
	v_lshl_add_u64 v[84:85], v[68:69], 0, v[0:1]
	v_bfe_u32 v0, v67, 16, 1
	global_store_dwordx4 v[84:85], v[62:65], off sc0 sc1
	v_add3_u32 v0, v67, v0, s62
	v_lshrrev_b32_e32 v0, 16, v0
	v_bfe_u32 v62, v71, 16, 1
	v_add3_u32 v62, v71, v62, s62
	v_and_or_b32 v62, v62, s63, v0
	v_bfe_u32 v0, v73, 16, 1
	v_add3_u32 v0, v73, v0, s62
	v_bfe_u32 v63, v75, 16, 1
	v_lshrrev_b32_e32 v0, 16, v0
	v_add3_u32 v63, v75, v63, s62
	v_and_or_b32 v63, v63, s63, v0
	v_bfe_u32 v0, v77, 16, 1
	v_add3_u32 v0, v77, v0, s62
	v_bfe_u32 v64, v79, 16, 1
	v_lshrrev_b32_e32 v0, 16, v0
	v_add3_u32 v64, v79, v64, s62
	v_and_or_b32 v64, v64, s63, v0
	v_bfe_u32 v0, v81, 16, 1
	v_add3_u32 v0, v81, v0, s62
	v_bfe_u32 v65, v83, 16, 1
	v_lshrrev_b32_e32 v0, 16, v0
	v_add3_u32 v65, v83, v65, s62
	v_bitop3_b32 v66, s4, v58, v51 bitop3:0xc8
	v_and_or_b32 v65, v65, s63, v0
	v_or_b32_e32 v0, s4, v51
	v_or_b32_e32 v66, s8, v66
	v_cndmask_b32_e32 v0, v0, v66, vcc
	v_lshlrev_b32_e32 v0, 11, v0
	ds_read2_b32 v[66:67], v50 offset0:16 offset1:24
	v_lshl_add_u64 v[70:71], v[68:69], 0, v[0:1]
	global_store_dwordx4 v[70:71], v[62:65], off sc0 sc1
	ds_read2_b32 v[70:71], v50 offset0:49 offset1:57
	ds_read2_b32 v[72:73], v50 offset0:82 offset1:90
	ds_read2_b32 v[74:75], v50 offset0:115 offset1:123
	s_waitcnt lgkmcnt(3)
	v_bfe_u32 v0, v66, 16, 1
	v_add3_u32 v0, v66, v0, s62
	s_waitcnt lgkmcnt(2)
	v_bfe_u32 v62, v70, 16, 1
	ds_read2_b32 v[76:77], v50 offset0:148 offset1:156
	v_lshrrev_b32_e32 v0, 16, v0
	v_add3_u32 v62, v70, v62, s62
	ds_read2_b32 v[78:79], v50 offset0:181 offset1:189
	v_and_or_b32 v62, v62, s63, v0
	s_waitcnt lgkmcnt(3)
	v_bfe_u32 v0, v72, 16, 1
	v_add3_u32 v0, v72, v0, s62
	s_waitcnt lgkmcnt(2)
	v_bfe_u32 v63, v74, 16, 1
	ds_read2_b32 v[80:81], v50 offset0:214 offset1:222
	v_lshrrev_b32_e32 v0, 16, v0
	v_add3_u32 v63, v74, v63, s62
	ds_read2_b32 v[82:83], v50 offset0:247 offset1:255
	v_and_or_b32 v63, v63, s63, v0
	s_waitcnt lgkmcnt(3)
	v_bfe_u32 v0, v76, 16, 1
	v_add3_u32 v0, v76, v0, s62
	s_waitcnt lgkmcnt(2)
	v_bfe_u32 v64, v78, 16, 1
	v_lshrrev_b32_e32 v0, 16, v0
	v_add3_u32 v64, v78, v64, s62
	v_and_or_b32 v64, v64, s63, v0
	s_waitcnt lgkmcnt(1)
	v_bfe_u32 v0, v80, 16, 1
	v_add3_u32 v0, v80, v0, s62
	s_waitcnt lgkmcnt(0)
	v_bfe_u32 v65, v82, 16, 1
	v_lshrrev_b32_e32 v0, 16, v0
	v_add3_u32 v65, v82, v65, s62
	v_bitop3_b32 v66, s4, v59, v52 bitop3:0xc8
	v_and_or_b32 v65, v65, s63, v0
	v_or_b32_e32 v0, s4, v52
	v_or_b32_e32 v66, s8, v66
	v_cndmask_b32_e32 v0, v0, v66, vcc
	v_lshlrev_b32_e32 v0, 11, v0
	v_lshl_add_u64 v[84:85], v[68:69], 0, v[0:1]
	global_store_dwordx4 v[84:85], v[62:65], off sc0 sc1
	v_or_b32_e32 v0, s4, v53
	v_bfe_u32 v66, v81, 16, 1
	v_bitop3_b32 v62, s4, v60, v53 bitop3:0xc8
	v_or_b32_e32 v62, s8, v62
	v_bfe_u32 v63, v67, 16, 1
	v_cndmask_b32_e32 v0, v0, v62, vcc
	v_bfe_u32 v62, v71, 16, 1
	v_add3_u32 v63, v67, v63, s62
	v_add3_u32 v62, v71, v62, s62
	v_lshrrev_b32_e32 v63, 16, v63
	v_bfe_u32 v64, v73, 16, 1
	v_and_or_b32 v62, v62, s63, v63
	v_bfe_u32 v63, v75, 16, 1
	v_add3_u32 v64, v73, v64, s62
	v_add3_u32 v63, v75, v63, s62
	v_lshrrev_b32_e32 v64, 16, v64
	v_bfe_u32 v65, v77, 16, 1
	v_and_or_b32 v63, v63, s63, v64
	v_bfe_u32 v64, v79, 16, 1
	v_add3_u32 v65, v77, v65, s62
	v_add3_u32 v64, v79, v64, s62
	v_lshrrev_b32_e32 v65, 16, v65
	v_and_or_b32 v64, v64, s63, v65
	v_bfe_u32 v65, v83, 16, 1
	v_add3_u32 v66, v81, v66, s62
	v_add3_u32 v65, v83, v65, s62
	v_lshrrev_b32_e32 v66, 16, v66
	v_lshlrev_b32_e32 v0, 11, v0
	v_and_or_b32 v65, v65, s63, v66
	v_lshl_add_u64 v[66:67], v[68:69], 0, v[0:1]
	global_store_dwordx4 v[66:67], v[62:65], off sc0 sc1
	s_waitcnt lgkmcnt(0)

.LBB0_40:
	s_andn2_b64 vcc, exec, s[4:5]
	s_cbranch_vccnz .LBB0_33
	s_mul_hi_i32 s0, s3, 0x2e8ba2e9
	s_lshr_b32 s4, s0, 31
	s_ashr_i32 s0, s0, 5
	s_add_i32 s0, s0, s4
	s_lshl_b32 s4, s0, 6
	s_mulk_i32 s0, 0xea00
	s_add_i32 s8, s11, s0
	s_ashr_i32 s9, s8, 31
	v_lshl_add_u64 v[62:63], s[8:9], 2, v[12:13]
	v_or_b32_e32 v0, s4, v14
	v_mad_i64_i32 v[64:65], s[66:67], v0, s64, v[62:63]
	v_or_b32_e32 v0, s4, v16
	v_mad_i64_i32 v[66:67], s[66:67], v0, s64, v[62:63]
	v_or_b32_e32 v0, s4, v17
	v_mad_i64_i32 v[68:69], s[66:67], v0, s64, v[62:63]
	v_or_b32_e32 v0, s4, v18
	v_mad_i64_i32 v[70:71], s[66:67], v0, s64, v[62:63]
	v_or_b32_e32 v0, s4, v19
	v_mad_i64_i32 v[72:73], s[66:67], v0, s64, v[62:63]
	v_or_b32_e32 v0, s4, v20
	v_mad_i64_i32 v[74:75], s[66:67], v0, s64, v[62:63]
	v_or_b32_e32 v0, s4, v21
	v_mad_i64_i32 v[76:77], s[66:67], v0, s64, v[62:63]
	v_or_b32_e32 v0, s4, v22
	v_mad_i64_i32 v[78:79], s[66:67], v0, s64, v[62:63]
	global_load_dword v0, v[64:65], off nt
	global_load_dword v84, v[66:67], off nt
	global_load_dword v85, v[68:69], off nt
	global_load_dword v86, v[70:71], off nt
	global_load_dword v87, v[72:73], off nt
	global_load_dword v88, v[74:75], off nt
	global_load_dword v89, v[76:77], off nt
	global_load_dword v90, v[78:79], off nt
	v_or_b32_e32 v64, s4, v23
	v_or_b32_e32 v68, s4, v25
	v_or_b32_e32 v70, s4, v26
	v_or_b32_e32 v72, s4, v27
	v_or_b32_e32 v74, s4, v29
	v_or_b32_e32 v78, s4, v31
	v_mad_i64_i32 v[64:65], s[66:67], v64, s64, v[62:63]
	v_or_b32_e32 v66, s4, v24
	v_or_b32_e32 v76, s4, v30
	v_mad_i64_i32 v[68:69], s[66:67], v68, s64, v[62:63]
	v_mad_i64_i32 v[70:71], s[66:67], v70, s64, v[62:63]
	v_mad_i64_i32 v[72:73], s[66:67], v72, s64, v[62:63]
	v_mad_i64_i32 v[74:75], s[66:67], v74, s64, v[62:63]
	v_mad_i64_i32 v[78:79], s[66:67], v78, s64, v[62:63]
	v_mad_i64_i32 v[66:67], s[66:67], v66, s64, v[62:63]
	v_or_b32_e32 v80, s4, v32
	v_or_b32_e32 v82, s4, v33
	v_or_b32_e32 v91, s4, v34
	v_or_b32_e32 v92, s4, v36
	v_mad_i64_i32 v[76:77], s[66:67], v76, s64, v[62:63]
	global_load_dword v93, v[64:65], off nt
	global_load_dword v94, v[66:67], off nt
	global_load_dword v95, v[68:69], off nt
	global_load_dword v96, v[70:71], off nt
	global_load_dword v97, v[72:73], off nt
	global_load_dword v98, v[74:75], off nt
	global_load_dword v99, v[76:77], off nt
	s_nop 0
	global_load_dword v78, v[78:79], off nt
	v_or_b32_e32 v68, s4, v37
	v_or_b32_e32 v70, s4, v38
	v_or_b32_e32 v72, s4, v39
	v_or_b32_e32 v74, s4, v40
	v_mad_i64_i32 v[80:81], s[66:67], v80, s64, v[62:63]
	v_mad_i64_i32 v[82:83], s[66:67], v82, s64, v[62:63]
	v_mad_i64_i32 v[64:65], s[66:67], v91, s64, v[62:63]
	v_mad_i64_i32 v[66:67], s[66:67], v92, s64, v[62:63]
	v_mad_i64_i32 v[68:69], s[66:67], v68, s64, v[62:63]
	v_mad_i64_i32 v[70:71], s[66:67], v70, s64, v[62:63]
	v_mad_i64_i32 v[72:73], s[66:67], v72, s64, v[62:63]
	v_mad_i64_i32 v[74:75], s[66:67], v74, s64, v[62:63]
	global_load_dword v79, v[80:81], off nt
	s_nop 0
	global_load_dword v80, v[82:83], off nt
	global_load_dword v81, v[64:65], off nt
	s_nop 0
	global_load_dword v82, v[66:67], off nt
	global_load_dword v83, v[68:69], off nt
	global_load_dword v91, v[70:71], off nt
	global_load_dword v92, v[72:73], off nt
	global_load_dword v100, v[74:75], off nt
	v_or_b32_e32 v64, s4, v41
	v_or_b32_e32 v66, s4, v42
	v_or_b32_e32 v68, s4, v43
	v_or_b32_e32 v70, s4, v44
	v_or_b32_e32 v72, s4, v45
	v_or_b32_e32 v74, s4, v46
	v_or_b32_e32 v76, s4, v47
	v_or_b32_e32 v101, s4, v48
	v_mad_i64_i32 v[64:65], s[66:67], v64, s64, v[62:63]
	v_mad_i64_i32 v[66:67], s[66:67], v66, s64, v[62:63]
	v_mad_i64_i32 v[68:69], s[66:67], v68, s64, v[62:63]
	v_mad_i64_i32 v[70:71], s[66:67], v70, s64, v[62:63]
	v_mad_i64_i32 v[72:73], s[66:67], v72, s64, v[62:63]
	v_mad_i64_i32 v[74:75], s[66:67], v74, s64, v[62:63]
	v_mad_i64_i32 v[76:77], s[66:67], v76, s64, v[62:63]
	v_mad_i64_i32 v[62:63], s[66:67], v101, s64, v[62:63]
	global_load_dword v64, v[64:65], off nt
	s_nop 0
	global_load_dword v65, v[66:67], off nt
	s_nop 0
	global_load_dword v66, v[68:69], off nt
	global_load_dword v67, v[70:71], off nt
	s_nop 0
	global_load_dword v68, v[72:73], off nt
	global_load_dword v69, v[74:75], off nt
	global_load_dword v70, v[76:77], off nt
	s_nop 0
	global_load_dword v62, v[62:63], off nt
	s_waitcnt vmcnt(30)
	ds_write2_b32 v54, v0, v84 offset1:66
	s_waitcnt vmcnt(28)
	ds_write2_b32 v54, v85, v86 offset0:132 offset1:198
	s_waitcnt vmcnt(26)
	ds_write2_b32 v55, v87, v88 offset0:8 offset1:74
	s_waitcnt vmcnt(24)
	ds_write2_b32 v56, v89, v90 offset1:66
	s_waitcnt vmcnt(22)
	ds_write2_b32 v56, v93, v94 offset0:132 offset1:198
	v_add_u32_e32 v0, 0x400, v56
	s_waitcnt vmcnt(20)
	ds_write2_b32 v0, v95, v96 offset0:8 offset1:74
	v_add_u32_e32 v0, v15, v28
	s_waitcnt vmcnt(18)
	ds_write2_b32 v0, v97, v98 offset1:66
	s_waitcnt vmcnt(16)
	ds_write2_b32 v0, v99, v78 offset0:132 offset1:198
	v_add_u32_e32 v0, 0x400, v0
	s_ashr_i32 s5, s4, 31
	v_lshl_add_u64 v[84:85], s[4:5], 1, v[2:3]
	s_waitcnt vmcnt(14)
	ds_write2_b32 v0, v79, v80 offset0:8 offset1:74
	v_add_u32_e32 v0, v15, v35
	v_add_u32_e32 v63, 0x400, v0
	s_waitcnt vmcnt(12)
	ds_write2_b32 v0, v81, v82 offset1:66
	s_waitcnt vmcnt(10)
	ds_write2_b32 v0, v83, v91 offset0:132 offset1:198
	s_waitcnt vmcnt(8)
	ds_write2_b32 v63, v92, v100 offset0:8 offset1:74
	s_waitcnt vmcnt(6)
	ds_write2_b32 v63, v64, v65 offset0:140 offset1:206
	v_add_u32_e32 v63, 0x800, v0
	v_add_u32_e32 v0, 0xc00, v0
	s_waitcnt vmcnt(4)
	ds_write2_b32 v63, v66, v67 offset0:16 offset1:82
	s_waitcnt vmcnt(2)
	ds_write2_b32 v63, v68, v69 offset0:148 offset1:214
	s_waitcnt vmcnt(0)
	ds_write2_b32 v0, v70, v62 offset0:24 offset1:90
	s_waitcnt lgkmcnt(0)
	ds_read2_b32 v[66:67], v50 offset1:8
	ds_read2_b32 v[68:69], v50 offset0:33 offset1:41
	ds_read2_b32 v[70:71], v50 offset0:66 offset1:74
	ds_read2_b32 v[72:73], v50 offset0:99 offset1:107
	ds_read2_b32 v[74:75], v50 offset0:132 offset1:140
	s_waitcnt lgkmcnt(4)
	v_bfe_u32 v0, v66, 16, 1
	v_add3_u32 v0, v66, v0, s62
	s_waitcnt lgkmcnt(3)
	v_bfe_u32 v62, v68, 16, 1
	v_lshrrev_b32_e32 v0, 16, v0
	v_add3_u32 v62, v68, v62, s62
	ds_read2_b32 v[76:77], v50 offset0:165 offset1:173
	v_and_or_b32 v62, v62, s63, v0
	s_waitcnt lgkmcnt(3)
	v_bfe_u32 v0, v70, 16, 1
	v_add3_u32 v0, v70, v0, s62
	s_waitcnt lgkmcnt(2)
	v_bfe_u32 v63, v72, 16, 1
	ds_read2_b32 v[78:79], v50 offset0:198 offset1:206
	v_lshrrev_b32_e32 v0, 16, v0
	v_add3_u32 v63, v72, v63, s62
	ds_read2_b32 v[80:81], v50 offset0:231 offset1:239
	v_and_or_b32 v63, v63, s63, v0
	s_waitcnt lgkmcnt(3)
	v_bfe_u32 v0, v74, 16, 1
	v_add3_u32 v0, v74, v0, s62
	s_waitcnt lgkmcnt(2)
	v_bfe_u32 v64, v76, 16, 1
	v_lshrrev_b32_e32 v0, 16, v0
	v_add3_u32 v64, v76, v64, s62
	v_and_or_b32 v64, v64, s63, v0
	s_waitcnt lgkmcnt(1)
	v_bfe_u32 v0, v78, 16, 1
	v_add3_u32 v0, v78, v0, s62
	s_waitcnt lgkmcnt(0)
	v_bfe_u32 v65, v80, 16, 1
	v_lshrrev_b32_e32 v0, 16, v0
	v_add3_u32 v65, v80, v65, s62
	v_and_or_b32 v65, v65, s63, v0
	v_add_u32_e32 v0, s8, v49
	v_add_u32_e32 v66, 0xfffff500, v0
	v_cmp_lt_i32_e32 vcc, s61, v0
	s_nop 1
	v_cndmask_b32_e32 v66, v0, v66, vcc
	v_lshlrev_b32_e32 v68, 1, v66
	v_and_b32_e32 v68, 0xffffff00, v68
	v_and_b32_e32 v66, 0x67, v66
	v_cndmask_b32_e32 v70, 0, v61, vcc
	v_or3_b32 v82, v66, v70, v68
	v_ashrrev_i32_e32 v83, 31, v82
	v_lshlrev_b64 v[82:83], 11, v[82:83]
	v_lshl_add_u64 v[82:83], v[84:85], 0, v[82:83]
	global_store_dwordx4 v[82:83], v[62:65], off sc0 sc1
	v_bfe_u32 v66, v81, 16, 1
	v_add3_u32 v66, v81, v66, s62
	v_bfe_u32 v62, v67, 16, 1
	v_add3_u32 v62, v67, v62, s62
	v_bfe_u32 v63, v69, 16, 1
	v_lshrrev_b32_e32 v62, 16, v62
	v_add3_u32 v63, v69, v63, s62
	v_and_or_b32 v62, v63, s63, v62
	v_bfe_u32 v63, v71, 16, 1
	v_add3_u32 v63, v71, v63, s62
	v_bfe_u32 v64, v73, 16, 1
	v_lshrrev_b32_e32 v63, 16, v63
	v_add3_u32 v64, v73, v64, s62
	v_and_or_b32 v63, v64, s63, v63
	v_bfe_u32 v64, v75, 16, 1
	v_add3_u32 v64, v75, v64, s62
	v_bfe_u32 v65, v77, 16, 1
	v_lshrrev_b32_e32 v64, 16, v64
	v_add3_u32 v65, v77, v65, s62
	v_and_or_b32 v64, v65, s63, v64
	v_bfe_u32 v65, v79, 16, 1
	v_add3_u32 v65, v79, v65, s62
	v_lshrrev_b32_e32 v65, 16, v65
	v_and_or_b32 v65, v66, s63, v65
	v_add_u32_e32 v66, 8, v0
	v_add_u32_e32 v67, 0xfffff508, v0
	v_cmp_lt_i32_e32 vcc, s61, v66
	ds_read2_b32 v[70:71], v50 offset0:82 offset1:90
	ds_read2_b32 v[72:73], v50 offset0:115 offset1:123
	v_cndmask_b32_e32 v66, v66, v67, vcc
	v_lshlrev_b32_e32 v67, 1, v66
	v_and_b32_e32 v67, 0xffffff00, v67
	v_cndmask_b32_e32 v68, 0, v61, vcc
	v_and_b32_e32 v66, 0x6f, v66
	v_or3_b32 v66, v66, v68, v67
	v_ashrrev_i32_e32 v67, 31, v66
	v_lshlrev_b64 v[66:67], 11, v[66:67]
	ds_read2_b32 v[68:69], v50 offset0:16 offset1:24
	v_lshl_add_u64 v[66:67], v[84:85], 0, v[66:67]
	global_store_dwordx4 v[66:67], v[62:65], off sc0 sc1
	ds_read2_b32 v[66:67], v50 offset0:49 offset1:57
	ds_read2_b32 v[74:75], v50 offset0:148 offset1:156
	s_waitcnt lgkmcnt(2)
	v_bfe_u32 v62, v68, 16, 1
	v_add3_u32 v62, v68, v62, s62
	v_lshrrev_b32_e32 v62, 16, v62
	s_waitcnt lgkmcnt(1)
	v_bfe_u32 v63, v66, 16, 1
	v_add3_u32 v63, v66, v63, s62
	ds_read2_b32 v[76:77], v50 offset0:181 offset1:189
	v_and_or_b32 v62, v63, s63, v62
	v_bfe_u32 v63, v70, 16, 1
	v_add3_u32 v63, v70, v63, s62
	v_bfe_u32 v64, v72, 16, 1
	ds_read2_b32 v[78:79], v50 offset0:214 offset1:222
	v_lshrrev_b32_e32 v63, 16, v63
	v_add3_u32 v64, v72, v64, s62
	ds_read2_b32 v[80:81], v50 offset0:247 offset1:255
	v_and_or_b32 v63, v64, s63, v63
	s_waitcnt lgkmcnt(3)
	v_bfe_u32 v64, v74, 16, 1
	v_add3_u32 v64, v74, v64, s62
	s_waitcnt lgkmcnt(2)
	v_bfe_u32 v65, v76, 16, 1
	v_lshrrev_b32_e32 v64, 16, v64
	v_add3_u32 v65, v76, v65, s62
	v_and_or_b32 v64, v65, s63, v64
	s_waitcnt lgkmcnt(1)
	v_bfe_u32 v65, v78, 16, 1
	v_add3_u32 v65, v78, v65, s62
	s_waitcnt lgkmcnt(0)
	v_bfe_u32 v66, v80, 16, 1
	v_lshrrev_b32_e32 v65, 16, v65
	v_add3_u32 v66, v80, v66, s62
	v_and_or_b32 v65, v66, s63, v65
	v_add_u32_e32 v66, 16, v0
	v_add_u32_e32 v68, 0xfffff510, v0
	v_cmp_lt_i32_e32 vcc, s61, v66
	s_nop 1
	v_cndmask_b32_e32 v66, v66, v68, vcc
	v_lshlrev_b32_e32 v68, 1, v66
	v_and_b32_e32 v68, 0xffffff00, v68
	v_and_b32_e32 v66, 0x77, v66
	v_cndmask_b32_e32 v70, 0, v61, vcc
	v_or3_b32 v82, v66, v70, v68
	v_ashrrev_i32_e32 v83, 31, v82
	v_lshlrev_b64 v[82:83], 11, v[82:83]
	v_lshl_add_u64 v[82:83], v[84:85], 0, v[82:83]
	global_store_dwordx4 v[82:83], v[62:65], off sc0 sc1
	s_nop 1
	v_add_u32_e32 v62, 24, v0
	v_add_u32_e32 v0, 0xfffff518, v0
	v_cmp_lt_i32_e32 vcc, s61, v62
	v_bfe_u32 v64, v75, 16, 1
	v_add3_u32 v64, v75, v64, s62
	v_cndmask_b32_e32 v0, v62, v0, vcc
	v_lshlrev_b32_e32 v62, 1, v0
	v_and_b32_e32 v62, 0xffffff00, v62
	v_cndmask_b32_e32 v63, 0, v61, vcc
	v_and_b32_e32 v0, 0x7f, v0
	v_or3_b32 v66, v0, v63, v62
	v_bfe_u32 v62, v69, 16, 1
	v_bfe_u32 v0, v67, 16, 1
	v_add3_u32 v62, v69, v62, s62
	v_add3_u32 v0, v67, v0, s62
	v_lshrrev_b32_e32 v62, 16, v62
	v_bfe_u32 v63, v71, 16, 1
	v_and_or_b32 v62, v0, s63, v62
	v_bfe_u32 v0, v73, 16, 1
	v_add3_u32 v63, v71, v63, s62
	v_add3_u32 v0, v73, v0, s62
	v_lshrrev_b32_e32 v63, 16, v63
	v_and_or_b32 v63, v0, s63, v63
	v_bfe_u32 v0, v77, 16, 1
	v_add3_u32 v0, v77, v0, s62
	v_lshrrev_b32_e32 v64, 16, v64
	v_bfe_u32 v65, v79, 16, 1
	v_and_or_b32 v64, v0, s63, v64
	v_bfe_u32 v0, v81, 16, 1
	v_add3_u32 v65, v79, v65, s62
	v_ashrrev_i32_e32 v67, 31, v66
	v_add3_u32 v0, v81, v0, s62
	v_lshrrev_b32_e32 v65, 16, v65
	v_lshlrev_b64 v[66:67], 11, v[66:67]
	v_and_or_b32 v65, v0, s63, v65
	v_lshl_add_u64 v[66:67], v[84:85], 0, v[66:67]
	global_store_dwordx4 v[66:67], v[62:65], off sc0 sc1
	s_waitcnt lgkmcnt(0)
	s_branch .LBB0_33
